# P4 hg_out_item: item loads spread through the item instead of one 16-load burst after the first barrier; norm weights fetched early
# speedup vs baseline: 1.0177x; 1.0074x over previous
.LBB0_442:
	s_cmpk_gt_i32 s8, 0x7ff
	s_cbranch_scc1 .LBB0_459
	s_lshl_b32 s10, s8, 23
	s_and_b32 s10, s10, 0x1800000
	s_add_u32 s14, s86, s10
	s_addc_u32 s15, s87, 0
	s_add_u32 s10, s14, 0x8000000
	v_add_u32_e32 v74, 0x200, v70
	s_addc_u32 s11, s15, 0
	s_ashr_i32 s12, s8, 2
	v_ashrrev_i32_e32 v71, 31, v70
	v_ashrrev_i32_e32 v75, 31, v74
	s_ashr_i32 s13, s12, 31
	v_lshlrev_b64 v[66:67], 3, v[70:71]
	v_lshlrev_b64 v[68:69], 3, v[74:75]
	s_lshl_b64 s[12:13], s[12:13], 13
	s_waitcnt vmcnt(0)
	v_lshl_add_u64 v[2:3], s[12:13], 0, v[66:67]
	v_lshl_add_u64 v[4:5], s[12:13], 0, v[68:69]
	v_lshlrev_b64 v[22:23], 1, v[2:3]
	v_lshlrev_b64 v[24:25], 1, v[4:5]
	v_lshl_add_u64 v[2:3], s[10:11], 0, v[22:23]
	v_lshl_add_u64 v[6:7], s[10:11], 0, v[24:25]
	s_add_u32 s10, s14, 0xa000000
	s_addc_u32 s11, s15, 0
	global_load_dwordx4 v[2:5], v[2:3], off
	s_nop 0
	global_load_dwordx4 v[10:13], v[6:7], off
	v_lshl_add_u64 v[6:7], s[10:11], 0, v[22:23]
	v_lshl_add_u64 v[14:15], s[10:11], 0, v[24:25]
	s_add_u32 s10, s14, 0xc000000
	s_addc_u32 s11, s15, 0
	v_lshl_add_u64 v[18:19], s[10:11], 0, v[22:23]
	v_lshl_add_u64 v[26:27], s[10:11], 0, v[24:25]
	s_add_u32 s10, s14, 0xe000000
	s_addc_u32 s11, s15, 0
	v_lshl_add_u64 v[22:23], s[10:11], 0, v[22:23]
	v_lshl_add_u64 v[30:31], s[10:11], 0, v[24:25]
	v_lshlrev_b32_e32 v104, 3, v70
	v_ashrrev_i32_e32 v34, 4, v70
	s_movk_i32 s10, 0x88
	v_and_b32_e32 v0, 0x78, v104
	v_mul_lo_u32 v34, v34, s10
	v_add_lshl_u32 v34, v34, v0, 1
	v_readlane_b32 s14, v255, 16
	v_add_u32_e32 v109, 0, v34
	v_readlane_b32 s16, v255, 18
	v_add_u32_e32 v110, s14, v34
	v_ashrrev_i32_e32 v34, 4, v74
	v_mul_lo_u32 v34, v34, s10
	v_readlane_b32 s15, v255, 17
	s_movk_i32 s10, 0x100
	v_and_b32_e32 v102, 63, v70
	v_add_lshl_u32 v0, v34, v0, 1
	v_mov_b32_e32 v34, s16
	v_mov_b32_e32 v35, s15
	v_cmp_gt_u32_e64 s[40:41], s10, v70
	v_add_u32_e32 v111, 0, v0
	v_add_u32_e32 v112, s14, v0
	v_cndmask_b32_e64 v34, v34, v35, s[40:41]
	v_lshlrev_b32_e32 v35, 2, v102
	v_bfe_u32 v0, v70, 4, 2
	v_add_u32_e32 v113, v34, v35
	v_ashrrev_i32_e32 v34, 6, v70
	s_bfe_u32 s24, s3, 0x20006
	s_add_i32 s12, 0, 0x4400
	v_and_b32_e32 v133, -4, v34
	v_lshl_or_b32 v39, v34, 9, v180
	v_mov_b32_e32 v34, s12
	s_lshl_b32 s13, s24, 4
	v_lshlrev_b32_e32 v101, 2, v0
	v_and_b32_e32 v99, 15, v70
	v_cndmask_b32_e64 v135, v34, 0, s[40:41]
	v_or_b32_e32 v34, s13, v101
	s_lshl_b32 s25, s9, 4
	v_cmp_le_u32_e32 vcc, v34, v99
	s_cmp_lt_u32 s9, 4
	global_load_dwordx4 v[6:9], v[6:7], off
	s_nop 0
	global_load_dwordx4 v[14:17], v[14:15], off
	v_cndmask_b32_e64 v36, 0, 1, vcc
	v_cmp_ge_u32_e32 vcc, v34, v99
	global_load_dwordx4 v[18:21], v[18:19], off
	s_nop 0
	global_load_dwordx4 v[26:29], v[26:27], off
	v_cndmask_b32_e64 v37, 0, 1, vcc
	s_cselect_b64 vcc, -1, 0
	v_cndmask_b32_e32 v36, v37, v36, vcc
	global_load_dwordx4 v[22:25], v[22:23], off
	s_nop 0
	global_load_dwordx4 v[30:33], v[30:31], off
	v_and_b32_e32 v36, 1, v36
	v_cmp_eq_u32_e64 s[42:43], 1, v36
	v_or_b32_e32 v36, 1, v34
	v_cmp_lt_u32_e64 s[44:45], v34, v99
	v_or_b32_e32 v107, 16, v99
	v_cmp_le_u32_e64 s[50:51], v34, v107
	v_cndmask_b32_e64 v40, 0, 1, s[44:45]
	v_cmp_ge_u32_e64 s[44:45], v36, v99
	v_cmp_lt_u32_e64 s[52:53], v34, v107
	v_or_b32_e32 v105, 32, v99
	v_cndmask_b32_e64 v41, 0, 1, s[44:45]
	v_cndmask_b32_e32 v40, v41, v40, vcc
	v_and_b32_e32 v40, 1, v40
	v_cmp_eq_u32_e64 s[44:45], 1, v40
	v_or_b32_e32 v40, 2, v34
	v_cmp_le_u32_e64 s[46:47], v40, v99
	v_cmp_le_u32_e64 s[54:55], v40, v107
	v_cmp_le_u32_e64 s[58:59], v34, v105
	v_cndmask_b32_e64 v41, 0, 1, s[46:47]
	v_cmp_ge_u32_e64 s[46:47], v40, v99
	v_cmp_lt_u32_e64 s[60:61], v34, v105
	v_cmp_le_u32_e64 s[62:63], v40, v105
	v_cndmask_b32_e64 v42, 0, 1, s[46:47]
	v_cndmask_b32_e32 v41, v42, v41, vcc
	v_and_b32_e32 v41, 1, v41
	v_cmp_eq_u32_e64 s[46:47], 1, v41
	v_or_b32_e32 v41, 3, v34
	v_cmp_le_u32_e64 s[48:49], v41, v99
	v_cmp_le_u32_e64 s[56:57], v41, v107
	v_cmp_le_u32_e64 s[64:65], v41, v105
	v_cndmask_b32_e64 v42, 0, 1, s[48:49]
	v_cmp_ge_u32_e64 s[48:49], v41, v99
	v_or_b32_e32 v103, 48, v102
	v_cmp_le_u32_e64 s[66:67], v34, v103
	v_cndmask_b32_e64 v43, 0, 1, s[48:49]
	v_cndmask_b32_e32 v42, v43, v42, vcc
	v_and_b32_e32 v42, 1, v42
	v_cmp_eq_u32_e64 s[48:49], 1, v42
	v_cndmask_b32_e64 v42, 0, 1, s[50:51]
	v_cmp_ge_u32_e64 s[50:51], v34, v107
	v_cmp_lt_u32_e64 s[68:69], v34, v103
	v_cmp_le_u32_e64 s[70:71], v40, v103
	v_cndmask_b32_e64 v43, 0, 1, s[50:51]
	v_cndmask_b32_e32 v42, v43, v42, vcc
	v_and_b32_e32 v42, 1, v42
	v_cmp_eq_u32_e64 s[50:51], 1, v42
	v_cndmask_b32_e64 v42, 0, 1, s[52:53]
	v_cmp_ge_u32_e64 s[52:53], v36, v107
	v_cmp_le_u32_e64 s[72:73], v41, v103
	v_readlane_b32 s10, v255, 19
	v_cndmask_b32_e64 v43, 0, 1, s[52:53]
	v_cndmask_b32_e32 v42, v43, v42, vcc
	v_and_b32_e32 v42, 1, v42
	v_cmp_eq_u32_e64 s[52:53], 1, v42
	v_cndmask_b32_e64 v42, 0, 1, s[54:55]
	v_cmp_ge_u32_e64 s[54:55], v40, v107
	v_lshl_add_u32 v134, v102, 3, s10
	s_and_b64 s[10:11], vcc, exec
	v_cndmask_b32_e64 v43, 0, 1, s[54:55]
	v_cndmask_b32_e32 v42, v43, v42, vcc
	v_and_b32_e32 v42, 1, v42
	v_cmp_eq_u32_e64 s[54:55], 1, v42
	v_cndmask_b32_e64 v42, 0, 1, s[56:57]
	v_cmp_ge_u32_e64 s[56:57], v41, v107
	v_or_b32_e32 v37, s13, v99
	s_cselect_b32 s11, s15, s16
	v_cndmask_b32_e64 v43, 0, 1, s[56:57]
	v_cndmask_b32_e32 v42, v43, v42, vcc
	v_and_b32_e32 v42, 1, v42
	v_cmp_eq_u32_e64 s[56:57], 1, v42
	v_cndmask_b32_e64 v42, 0, 1, s[58:59]
	v_cmp_ge_u32_e64 s[58:59], v34, v105
	v_mul_u32_u24_e32 v37, 0x110, v37
	v_and_b32_e32 v72, 48, v70
	v_cndmask_b32_e64 v43, 0, 1, s[58:59]
	v_cndmask_b32_e32 v42, v43, v42, vcc
	v_and_b32_e32 v42, 1, v42
	v_cmp_eq_u32_e64 s[58:59], 1, v42
	v_cndmask_b32_e64 v42, 0, 1, s[60:61]
	v_cmp_ge_u32_e64 s[60:61], v36, v105
	v_lshlrev_b32_e32 v100, 3, v0
	s_cselect_b32 s10, 0, s12
	v_cndmask_b32_e64 v43, 0, 1, s[60:61]
	v_cndmask_b32_e32 v42, v43, v42, vcc
	v_and_b32_e32 v42, 1, v42
	v_cmp_eq_u32_e64 s[60:61], 1, v42
	v_cndmask_b32_e64 v42, 0, 1, s[62:63]
	v_cmp_ge_u32_e64 s[62:63], v40, v105
	v_add3_u32 v136, s11, v37, v72
	v_readlane_b32 s11, v255, 20
	v_cndmask_b32_e64 v43, 0, 1, s[62:63]
	v_cndmask_b32_e32 v42, v43, v42, vcc
	v_and_b32_e32 v42, 1, v42
	v_cmp_eq_u32_e64 s[62:63], 1, v42
	v_cndmask_b32_e64 v42, 0, 1, s[64:65]
	v_cmp_ge_u32_e64 s[64:65], v41, v105
	v_readlane_b32 s12, v255, 21
	v_add_u32_e32 v137, s10, v72
	v_cndmask_b32_e64 v43, 0, 1, s[64:65]
	v_cndmask_b32_e32 v42, v43, v42, vcc
	v_and_b32_e32 v42, 1, v42
	v_cmp_eq_u32_e64 s[64:65], 1, v42
	v_cndmask_b32_e64 v42, 0, 1, s[66:67]
	v_cmp_ge_u32_e64 s[66:67], v34, v103
	v_cndmask_b32_e64 v34, 0, 1, s[68:69]
	v_cmp_ge_u32_e64 s[68:69], v36, v103
	v_cndmask_b32_e64 v43, 0, 1, s[66:67]
	v_cndmask_b32_e32 v42, v43, v42, vcc
	v_cndmask_b32_e64 v36, 0, 1, s[68:69]
	v_cndmask_b32_e32 v34, v36, v34, vcc
	v_and_b32_e32 v34, 1, v34
	v_cmp_eq_u32_e64 s[68:69], 1, v34
	v_cndmask_b32_e64 v34, 0, 1, s[70:71]
	v_cmp_ge_u32_e64 s[70:71], v40, v103
	v_or_b32_e32 v37, 32, v100
	s_cselect_b32 s10, s11, s12
	v_cndmask_b32_e64 v36, 0, 1, s[70:71]
	v_cndmask_b32_e32 v34, v36, v34, vcc
	v_and_b32_e32 v34, 1, v34
	v_cmp_eq_u32_e64 s[70:71], 1, v34
	v_cndmask_b32_e64 v34, 0, 1, s[72:73]
	v_cmp_ge_u32_e64 s[72:73], v41, v103
	v_and_b32_e32 v42, 1, v42
	s_andn2_b32 s3, s3, 63
	v_cndmask_b32_e64 v36, 0, 1, s[72:73]
	v_cndmask_b32_e32 v34, v36, v34, vcc
	v_and_b32_e32 v34, 1, v34
	v_cmp_eq_u32_e64 s[72:73], 1, v34
	v_mul_u32_u24_e32 v34, 0x48, v99
	v_lshlrev_b32_e32 v34, 1, v34
	v_cmp_eq_u32_e64 s[66:67], 1, v42
	v_add_u32_e32 v36, s11, v72
	v_add_u32_e32 v41, s12, v72
	v_add_u32_e32 v42, 0x900, v34
	v_mul_u32_u24_e32 v44, 0x48, v103
	v_lshlrev_b32_e32 v125, 1, v37
	v_lshlrev_b32_e32 v117, 4, v70
	s_add_i32 s3, s3, 0
	v_bfe_u32 v108, v70, 2, 2
	v_add_u32_e32 v139, v36, v34
	v_add_u32_e32 v140, v41, v34
	v_add_u32_e32 v141, v36, v42
	v_add_u32_e32 v142, v41, v42
	v_add_u32_e32 v43, 0x1200, v34
	v_lshlrev_b32_e32 v44, 1, v44
	v_add3_u32 v153, s11, v34, v125
	v_add3_u32 v154, s12, v34, v125
	v_add3_u32 v155, s11, v42, v125
	v_add3_u32 v156, s12, v42, v125
	v_ashrrev_i32_e32 v76, 3, v70
	v_and_b32_e32 v34, 0x70, v117
	v_lshl_add_u32 v42, v99, 2, s3
	s_movk_i32 s3, 0x210
	v_add_u32_e32 v143, v36, v43
	v_add_u32_e32 v144, v41, v43
	v_add_u32_e32 v145, v36, v44
	v_or_b32_e32 v132, v37, v108
	v_add3_u32 v157, s11, v43, v125
	v_add3_u32 v158, s12, v43, v125
	v_mul_u32_u24_e32 v43, 0x840, v0
	v_mul_lo_u32 v36, v76, s3
	v_lshlrev_b32_e32 v0, 2, v34
	v_and_b32_e32 v37, 64, v215
	v_add3_u32 v162, 0, v36, v0
	v_xor_b32_e32 v36, 1, v215
	v_add_u32_e32 v37, 64, v37
	v_cmp_lt_i32_e32 vcc, v36, v37
	s_lshl_b32 s27, s9, 5
	s_lshl_b32 s26, s24, 5
	v_cndmask_b32_e32 v36, v215, v36, vcc
	v_lshlrev_b32_e32 v97, 2, v36
	v_xor_b32_e32 v36, 2, v215
	v_cmp_lt_i32_e32 vcc, v36, v37
	s_add_i32 s9, s14, s27
	v_and_b32_e32 v116, 12, v35
	v_cndmask_b32_e32 v36, v215, v36, vcc
	v_lshlrev_b32_e32 v98, 2, v36
	v_xor_b32_e32 v36, 4, v215
	v_cmp_lt_i32_e32 vcc, v36, v37
	v_or_b32_e32 v78, s25, v99
	s_add_i32 s10, s10, s26
	v_lshl_add_u32 v35, v116, 1, s9
	v_cndmask_b32_e32 v36, v215, v36, vcc
	s_ashr_i32 s9, s8, 31
	v_ashrrev_i32_e32 v79, 31, v78
	v_add_u32_e32 v138, s10, v100
	v_add3_u32 v159, s11, v44, v125
	v_lshlrev_b32_e32 v163, 2, v36
	s_lshl_b64 s[10:11], s[8:9], 16
	v_lshlrev_b64 v[36:37], 8, v[78:79]
	v_or_b32_e32 v114, v100, v108
	v_add3_u32 v160, s12, v44, v125
	v_readlane_b32 s12, v255, 27
	v_lshl_add_u64 v[36:37], s[10:11], 0, v[36:37]
	v_readlane_b32 s10, v255, 10
	v_lshlrev_b32_e32 v38, 9, v133
	v_mul_u32_u24_e32 v40, 0x110, v114
	v_add_u32_e32 v152, v41, v44
	v_mul_u32_u24_e32 v41, 0x110, v132
	v_readlane_b32 s14, v255, 29
	v_readlane_b32 s15, v255, 30
	v_or_b32_e32 v36, v36, v72
	v_readlane_b32 s11, v255, 11
	s_ashr_i32 s3, s2, 31
	v_cndmask_b32_e64 v115, 14, 1, s[40:41]
	v_cndmask_b32_e64 v118, 13, 2, s[40:41]
	v_cndmask_b32_e64 v119, 12, 3, s[40:41]
	v_cndmask_b32_e64 v120, 11, 4, s[40:41]
	v_cndmask_b32_e64 v121, 10, 5, s[40:41]
	v_cndmask_b32_e64 v122, 9, 6, s[40:41]
	v_cndmask_b32_e64 v123, 8, 7, s[40:41]
	v_cndmask_b32_e64 v124, 7, 8, s[40:41]
	v_cndmask_b32_e64 v126, 6, 9, s[40:41]
	v_cndmask_b32_e64 v127, 5, 10, s[40:41]
	v_cndmask_b32_e64 v128, 4, 11, s[40:41]
	v_cndmask_b32_e64 v129, 3, 12, s[40:41]
	v_cndmask_b32_e64 v130, 2, 13, s[40:41]
	v_cndmask_b32_e64 v131, 1, 14, s[40:41]
	v_mul_u32_u24_e32 v71, 0x110, v99
	v_mul_u32_u24_e32 v73, 0x110, v103
	v_mul_u32_u24_e32 v75, 0x90, v99
	v_mul_u32_u24_e32 v96, 0x90, v103
	v_add_u32_e32 v106, 0, v72
	v_ashrrev_i32_e32 v77, 31, v76
	v_lshl_add_u64 v[80:81], s[14:15], 0, v[0:1]
	v_lshl_add_u64 v[82:83], s[10:11], 0, v[36:37]
	s_lshl_b64 s[10:11], s[2:3], 16
	v_add_u32_e32 v79, v134, v39
	v_add_u32_e32 v164, v35, v40
	v_add_u32_e32 v165, v35, v41
	v_lshlrev_b32_e32 v0, 1, v34
	v_add_u32_e32 v166, v42, v43
	v_add_u32_e32 v167, v134, v38
	s_mov_b32 s29, s8
	v_readlane_b32 s13, v255, 28
	v_lshlrev_b32_e32 v236, 4, v214
	v_add_u32_e32 v237, 0x2000000, v236
	v_add_u32_e32 v238, 0x4000000, v236
	v_add_u32_e32 v239, 0x6000000, v236
	v_add_u32_e32 v240, 0x2000, v236
	v_add_u32_e32 v241, 0x2002000, v236
	v_add_u32_e32 v242, 0x4002000, v236
	v_add_u32_e32 v243, 0x6002000, v236
	s_waitcnt vmcnt(0)
	s_branch .LBB0_445
.LBB0_444:
	s_or_b64 exec, exec, s[14:15]
	v_mul_u32_u24_e32 v147, 0x44, v173
	v_lshl_add_u32 v147, v147, 2, v113
	ds_read_b32 v175, v147
	v_mad_u32_u24 v173, v173, s20, v102
	v_lshl_add_u32 v173, v173, 2, v135
	ds_read_b32 v177, v173
	s_ashr_i32 s14, s29, 2
	s_waitcnt lgkmcnt(1)
	v_lshlrev_b32_e32 v174, 16, v175
	v_and_b32_e32 v175, 0xffff0000, v175
	v_pk_add_f32 v[198:199], v[174:175], 1.0 op_sel_hi:[1,0] neg_lo:[1,0] neg_hi:[1,0]
	s_waitcnt lgkmcnt(0)
	v_lshlrev_b32_e32 v176, 16, v177
	v_pk_mul_f32 v[84:85], v[84:85], v[198:199]
	v_and_b32_e32 v177, 0xffff0000, v177
	v_max_f32_e32 v197, 0xda24260, v84
	v_rcp_f32_e32 v198, v197
	v_max_f32_e32 v197, 0xda24260, v85
	v_rcp_f32_e32 v199, v197
	s_ashr_i32 s15, s14, 31
	s_lshl_b64 vcc, s[14:15], 6
	s_and_b32 s14, s29, 3
	v_pk_mul_f32 v[174:175], v[198:199], v[174:175]
	s_lshl_b32 s15, s14, 23
	v_cvt_pk_bf16_f32 v174, v174, v175
	ds_write_b32 v147, v174
	v_pk_mul_f32 v[174:175], v[84:85], v[176:177]
	s_add_u32 s16, s86, s15
	v_cvt_pk_bf16_f32 v147, v174, v175
	ds_write_b32 v173, v147
	global_load_dwordx4 v[50:53], v[34:35], off
	v_mul_u32_u24_e32 v147, 0x44, v172
	v_lshl_add_u32 v147, v147, 2, v113
	ds_read_b32 v173, v147
	v_mad_u32_u24 v174, v172, s20, v102
	v_lshl_add_u32 v197, v174, 2, v135
	ds_read_b32 v175, v197
	s_addc_u32 s17, s87, 0
	s_waitcnt lgkmcnt(1)
	v_lshlrev_b32_e32 v172, 16, v173
	v_and_b32_e32 v173, 0xffff0000, v173
	v_pk_add_f32 v[176:177], v[172:173], 1.0 op_sel_hi:[1,0] neg_lo:[1,0] neg_hi:[1,0]
	s_waitcnt lgkmcnt(0)
	v_lshlrev_b32_e32 v174, 16, v175
	v_pk_mul_f32 v[84:85], v[84:85], v[176:177]
	v_and_b32_e32 v175, 0xffff0000, v175
	v_max_f32_e32 v176, 0xda24260, v84
	v_max_f32_e32 v177, 0xda24260, v85
	v_rcp_f32_e32 v176, v176
	v_rcp_f32_e32 v177, v177
	s_brev_b32 s15, 8
	s_lshl_b32 s80, s14, 9
	v_pk_mul_f32 v[172:173], v[176:177], v[172:173]
	s_mov_b32 s29, s28
	v_cvt_pk_bf16_f32 v172, v172, v173
	ds_write_b32 v147, v172
	v_pk_mul_f32 v[172:173], v[84:85], v[174:175]
	s_nop 0
	v_cvt_pk_bf16_f32 v147, v172, v173
	ds_write_b32 v197, v147
	global_load_dwordx4 v[46:49], v[82:83], off offset:-192
	v_mul_u32_u24_e32 v147, 0x44, v171
	v_lshl_add_u32 v147, v147, 2, v113
	ds_read_b32 v173, v147
	v_mad_u32_u24 v171, v171, s20, v102
	v_lshl_add_u32 v171, v171, 2, v135
	ds_read_b32 v175, v171
	s_waitcnt lgkmcnt(1)
	v_lshlrev_b32_e32 v172, 16, v173
	v_and_b32_e32 v173, 0xffff0000, v173
	v_pk_add_f32 v[176:177], v[172:173], 1.0 op_sel_hi:[1,0] neg_lo:[1,0] neg_hi:[1,0]
	s_waitcnt lgkmcnt(0)
	v_lshlrev_b32_e32 v174, 16, v175
	v_pk_mul_f32 v[84:85], v[84:85], v[176:177]
	v_and_b32_e32 v175, 0xffff0000, v175
	v_max_f32_e32 v176, 0xda24260, v84
	v_max_f32_e32 v177, 0xda24260, v85
	v_rcp_f32_e32 v176, v176
	v_rcp_f32_e32 v177, v177
	s_nop 0
	v_pk_mul_f32 v[172:173], v[176:177], v[172:173]
	s_nop 0
	v_cvt_pk_bf16_f32 v172, v172, v173
	ds_write_b32 v147, v172
	v_pk_mul_f32 v[172:173], v[84:85], v[174:175]
	s_nop 0
	v_cvt_pk_bf16_f32 v147, v172, v173
	ds_write_b32 v171, v147
	global_load_dwordx4 v[42:45], v[82:83], off offset:-128
	v_mul_u32_u24_e32 v147, 0x44, v170
	v_lshl_add_u32 v147, v147, 2, v113
	ds_read_b32 v171, v147
	v_mad_u32_u24 v172, v170, s20, v102
	v_lshl_add_u32 v176, v172, 2, v135
	ds_read_b32 v173, v176
	s_waitcnt lgkmcnt(1)
	v_lshlrev_b32_e32 v170, 16, v171
	v_and_b32_e32 v171, 0xffff0000, v171
	v_pk_add_f32 v[174:175], v[170:171], 1.0 op_sel_hi:[1,0] neg_lo:[1,0] neg_hi:[1,0]
	s_waitcnt lgkmcnt(0)
	v_lshlrev_b32_e32 v172, 16, v173
	v_pk_mul_f32 v[84:85], v[84:85], v[174:175]
	v_and_b32_e32 v173, 0xffff0000, v173
	v_max_f32_e32 v174, 0xda24260, v84
	v_max_f32_e32 v175, 0xda24260, v85
	v_rcp_f32_e32 v174, v174
	v_rcp_f32_e32 v175, v175
	s_nop 0
	v_pk_mul_f32 v[170:171], v[174:175], v[170:171]
	s_nop 0
	v_cvt_pk_bf16_f32 v170, v170, v171
	ds_write_b32 v147, v170
	v_pk_mul_f32 v[170:171], v[84:85], v[172:173]
	s_nop 0
	v_cvt_pk_bf16_f32 v147, v170, v171
	ds_write_b32 v176, v147
	global_load_dwordx4 v[38:41], v[82:83], off offset:-64
	v_mul_u32_u24_e32 v147, 0x44, v169
	v_lshl_add_u32 v147, v147, 2, v113
	ds_read_b32 v171, v147
	v_mad_u32_u24 v169, v169, s20, v102
	v_lshl_add_u32 v169, v169, 2, v135
	ds_read_b32 v173, v169
	v_add_u32_e32 v176, v137, v73
	s_waitcnt lgkmcnt(1)
	v_lshlrev_b32_e32 v170, 16, v171
	v_and_b32_e32 v171, 0xffff0000, v171
	v_pk_add_f32 v[174:175], v[170:171], 1.0 op_sel_hi:[1,0] neg_lo:[1,0] neg_hi:[1,0]
	s_waitcnt lgkmcnt(0)
	v_lshlrev_b32_e32 v172, 16, v173
	v_pk_mul_f32 v[84:85], v[84:85], v[174:175]
	v_and_b32_e32 v173, 0xffff0000, v173
	v_max_f32_e32 v174, 0xda24260, v84
	v_max_f32_e32 v175, 0xda24260, v85
	v_rcp_f32_e32 v174, v174
	v_rcp_f32_e32 v175, v175
	s_nop 0
	v_pk_mul_f32 v[170:171], v[174:175], v[170:171]
	s_nop 0
	v_cvt_pk_bf16_f32 v170, v170, v171
	ds_write_b32 v147, v170
	v_pk_mul_f32 v[170:171], v[84:85], v[172:173]
	s_nop 0
	v_cvt_pk_bf16_f32 v147, v170, v171
	ds_write_b32 v169, v147
	global_load_dwordx4 v[34:37], v[82:83], off
	v_lshl_add_u64 v[82:83], v[82:83], 0, s[10:11]
	v_mul_u32_u24_e32 v147, 0x44, v168
	v_lshl_add_u32 v147, v147, 2, v113
	ds_read_b32 v169, v147
	v_mad_u32_u24 v170, v168, s20, v102
	v_lshl_add_u32 v174, v170, 2, v135
	ds_read_b32 v171, v174
	s_waitcnt lgkmcnt(1)
	v_lshlrev_b32_e32 v168, 16, v169
	v_and_b32_e32 v169, 0xffff0000, v169
	v_pk_add_f32 v[172:173], v[168:169], 1.0 op_sel_hi:[1,0] neg_lo:[1,0] neg_hi:[1,0]
	s_waitcnt lgkmcnt(0)
	v_lshlrev_b32_e32 v170, 16, v171
	v_pk_mul_f32 v[84:85], v[84:85], v[172:173]
	v_and_b32_e32 v171, 0xffff0000, v171
	v_max_f32_e32 v172, 0xda24260, v84
	v_max_f32_e32 v173, 0xda24260, v85
	v_rcp_f32_e32 v172, v172
	v_rcp_f32_e32 v173, v173
	s_nop 0
	v_pk_mul_f32 v[168:169], v[172:173], v[168:169]
	s_nop 0
	v_cvt_pk_bf16_f32 v168, v168, v169
	ds_write_b32 v147, v168
	v_pk_mul_f32 v[168:169], v[84:85], v[170:171]
	s_nop 0
	v_cvt_pk_bf16_f32 v147, v168, v169
	ds_write_b32 v174, v147
	global_load_dwordx4 v[2:5], v236, s[98:99]
	v_mul_u32_u24_e32 v147, 0x44, v95
	v_lshl_add_u32 v147, v147, 2, v113
	ds_read_b32 v169, v147
	v_mad_u32_u24 v95, v95, s20, v102
	v_lshl_add_u32 v95, v95, 2, v135
	ds_read_b32 v171, v95
	s_waitcnt lgkmcnt(1)
	v_lshlrev_b32_e32 v168, 16, v169
	v_and_b32_e32 v169, 0xffff0000, v169
	v_pk_add_f32 v[172:173], v[168:169], 1.0 op_sel_hi:[1,0] neg_lo:[1,0] neg_hi:[1,0]
	s_waitcnt lgkmcnt(0)
	v_lshlrev_b32_e32 v170, 16, v171
	v_pk_mul_f32 v[84:85], v[84:85], v[172:173]
	v_and_b32_e32 v171, 0xffff0000, v171
	v_max_f32_e32 v172, 0xda24260, v84
	v_max_f32_e32 v173, 0xda24260, v85
	v_rcp_f32_e32 v172, v172
	v_rcp_f32_e32 v173, v173
	s_nop 0
	v_pk_mul_f32 v[168:169], v[172:173], v[168:169]
	s_nop 0
	v_cvt_pk_bf16_f32 v168, v168, v169
	ds_write_b32 v147, v168
	v_pk_mul_f32 v[168:169], v[84:85], v[170:171]
	s_nop 0
	v_cvt_pk_bf16_f32 v147, v168, v169
	ds_write_b32 v95, v147
	v_mul_u32_u24_e32 v95, 0x44, v94
	v_lshl_add_u32 v172, v95, 2, v113
	ds_read_b32 v95, v172
	v_mad_u32_u24 v147, v94, s20, v102
	v_lshl_add_u32 v147, v147, 2, v135
	ds_read_b32 v169, v147
	s_waitcnt lgkmcnt(1)
	v_lshlrev_b32_e32 v94, 16, v95
	v_and_b32_e32 v95, 0xffff0000, v95
	v_pk_add_f32 v[170:171], v[94:95], 1.0 op_sel_hi:[1,0] neg_lo:[1,0] neg_hi:[1,0]
	s_waitcnt lgkmcnt(0)
	v_lshlrev_b32_e32 v168, 16, v169
	v_pk_mul_f32 v[84:85], v[84:85], v[170:171]
	v_and_b32_e32 v169, 0xffff0000, v169
	v_max_f32_e32 v170, 0xda24260, v84
	v_max_f32_e32 v171, 0xda24260, v85
	v_rcp_f32_e32 v170, v170
	v_rcp_f32_e32 v171, v171
	s_nop 0
	v_pk_mul_f32 v[94:95], v[170:171], v[94:95]
	s_nop 0
	v_cvt_pk_bf16_f32 v94, v94, v95
	ds_write_b32 v172, v94
	v_pk_mul_f32 v[94:95], v[84:85], v[168:169]
	s_nop 0
	v_cvt_pk_bf16_f32 v94, v94, v95
	ds_write_b32 v147, v94
	global_load_dwordx4 v[6:9], v237, s[98:99]
	v_mul_u32_u24_e32 v94, 0x44, v93
	v_lshl_add_u32 v147, v94, 2, v113
	ds_read_b32 v95, v147
	v_mad_u32_u24 v93, v93, s20, v102
	v_lshl_add_u32 v93, v93, 2, v135
	ds_read_b32 v169, v93
	s_waitcnt lgkmcnt(1)
	v_lshlrev_b32_e32 v94, 16, v95
	v_and_b32_e32 v95, 0xffff0000, v95
	v_pk_add_f32 v[170:171], v[94:95], 1.0 op_sel_hi:[1,0] neg_lo:[1,0] neg_hi:[1,0]
	s_waitcnt lgkmcnt(0)
	v_lshlrev_b32_e32 v168, 16, v169
	v_pk_mul_f32 v[84:85], v[84:85], v[170:171]
	v_and_b32_e32 v169, 0xffff0000, v169
	v_max_f32_e32 v170, 0xda24260, v84
	v_max_f32_e32 v171, 0xda24260, v85
	v_rcp_f32_e32 v170, v170
	v_rcp_f32_e32 v171, v171
	s_nop 0
	v_pk_mul_f32 v[94:95], v[170:171], v[94:95]
	s_nop 0
	v_cvt_pk_bf16_f32 v94, v94, v95
	ds_write_b32 v147, v94
	v_pk_mul_f32 v[94:95], v[84:85], v[168:169]
	s_nop 0
	v_cvt_pk_bf16_f32 v94, v94, v95
	ds_write_b32 v93, v94
	v_mul_u32_u24_e32 v93, 0x44, v92
	v_lshl_add_u32 v147, v93, 2, v113
	ds_read_b32 v93, v147
	v_mad_u32_u24 v94, v92, s20, v102
	v_lshl_add_u32 v170, v94, 2, v135
	ds_read_b32 v95, v170
	s_waitcnt lgkmcnt(1)
	v_lshlrev_b32_e32 v92, 16, v93
	v_and_b32_e32 v93, 0xffff0000, v93
	v_pk_add_f32 v[168:169], v[92:93], 1.0 op_sel_hi:[1,0] neg_lo:[1,0] neg_hi:[1,0]
	s_waitcnt lgkmcnt(0)
	v_lshlrev_b32_e32 v94, 16, v95
	v_pk_mul_f32 v[84:85], v[84:85], v[168:169]
	v_and_b32_e32 v95, 0xffff0000, v95
	v_max_f32_e32 v168, 0xda24260, v84
	v_max_f32_e32 v169, 0xda24260, v85
	v_rcp_f32_e32 v168, v168
	v_rcp_f32_e32 v169, v169
	s_nop 0
	v_pk_mul_f32 v[92:93], v[168:169], v[92:93]
	s_nop 0
	v_cvt_pk_bf16_f32 v92, v92, v93
	ds_write_b32 v147, v92
	v_pk_mul_f32 v[92:93], v[84:85], v[94:95]
	s_nop 0
	v_cvt_pk_bf16_f32 v92, v92, v93
	ds_write_b32 v170, v92
	global_load_dwordx4 v[18:21], v238, s[98:99]
	v_mul_u32_u24_e32 v92, 0x44, v91
	v_lshl_add_u32 v147, v92, 2, v113
	ds_read_b32 v93, v147
	v_mad_u32_u24 v91, v91, s20, v102
	v_lshl_add_u32 v91, v91, 2, v135
	ds_read_b32 v95, v91
	s_waitcnt lgkmcnt(1)
	v_lshlrev_b32_e32 v92, 16, v93
	v_and_b32_e32 v93, 0xffff0000, v93
	v_pk_add_f32 v[168:169], v[92:93], 1.0 op_sel_hi:[1,0] neg_lo:[1,0] neg_hi:[1,0]
	s_waitcnt lgkmcnt(0)
	v_lshlrev_b32_e32 v94, 16, v95
	v_pk_mul_f32 v[84:85], v[84:85], v[168:169]
	v_and_b32_e32 v95, 0xffff0000, v95
	v_max_f32_e32 v168, 0xda24260, v84
	v_max_f32_e32 v169, 0xda24260, v85
	v_rcp_f32_e32 v168, v168
	v_rcp_f32_e32 v169, v169
	s_nop 0
	v_pk_mul_f32 v[92:93], v[168:169], v[92:93]
	s_nop 0
	v_cvt_pk_bf16_f32 v92, v92, v93
	ds_write_b32 v147, v92
	v_pk_mul_f32 v[92:93], v[84:85], v[94:95]
	s_nop 0
	v_cvt_pk_bf16_f32 v92, v92, v93
	ds_write_b32 v91, v92
	v_mul_u32_u24_e32 v91, 0x44, v90
	v_lshl_add_u32 v147, v91, 2, v113
	ds_read_b32 v91, v147
	v_mad_u32_u24 v92, v90, s20, v102
	v_lshl_add_u32 v168, v92, 2, v135
	ds_read_b32 v93, v168
	s_waitcnt lgkmcnt(1)
	v_lshlrev_b32_e32 v90, 16, v91
	v_and_b32_e32 v91, 0xffff0000, v91
	v_pk_add_f32 v[94:95], v[90:91], 1.0 op_sel_hi:[1,0] neg_lo:[1,0] neg_hi:[1,0]
	s_waitcnt lgkmcnt(0)
	v_lshlrev_b32_e32 v92, 16, v93
	v_pk_mul_f32 v[84:85], v[84:85], v[94:95]
	v_and_b32_e32 v93, 0xffff0000, v93
	v_max_f32_e32 v94, 0xda24260, v84
	v_max_f32_e32 v95, 0xda24260, v85
	v_rcp_f32_e32 v94, v94
	v_rcp_f32_e32 v95, v95
	s_nop 0
	v_pk_mul_f32 v[90:91], v[94:95], v[90:91]
	s_nop 0
	v_cvt_pk_bf16_f32 v90, v90, v91
	ds_write_b32 v147, v90
	v_pk_mul_f32 v[90:91], v[84:85], v[92:93]
	s_nop 0
	v_cvt_pk_bf16_f32 v90, v90, v91
	ds_write_b32 v168, v90
	global_load_dwordx4 v[22:25], v239, s[98:99]
	v_mul_u32_u24_e32 v90, 0x44, v89
	v_lshl_add_u32 v147, v90, 2, v113
	ds_read_b32 v91, v147
	v_mad_u32_u24 v89, v89, s20, v102
	v_lshl_add_u32 v89, v89, 2, v135
	ds_read_b32 v93, v89
	s_waitcnt lgkmcnt(1)
	v_lshlrev_b32_e32 v90, 16, v91
	v_and_b32_e32 v91, 0xffff0000, v91
	v_pk_add_f32 v[94:95], v[90:91], 1.0 op_sel_hi:[1,0] neg_lo:[1,0] neg_hi:[1,0]
	s_waitcnt lgkmcnt(0)
	v_lshlrev_b32_e32 v92, 16, v93
	v_pk_mul_f32 v[84:85], v[84:85], v[94:95]
	v_and_b32_e32 v93, 0xffff0000, v93
	v_max_f32_e32 v94, 0xda24260, v84
	v_max_f32_e32 v95, 0xda24260, v85
	v_rcp_f32_e32 v94, v94
	v_rcp_f32_e32 v95, v95
	s_nop 0
	v_pk_mul_f32 v[90:91], v[94:95], v[90:91]
	s_nop 0
	v_cvt_pk_bf16_f32 v90, v90, v91
	ds_write_b32 v147, v90
	v_pk_mul_f32 v[90:91], v[84:85], v[92:93]
	v_add_u32_e32 v147, v137, v71
	v_cvt_pk_bf16_f32 v90, v90, v91
	ds_write_b32 v89, v90
	v_mul_u32_u24_e32 v89, 0x44, v88
	v_lshl_add_u32 v94, v89, 2, v113
	ds_read_b32 v89, v94
	v_mad_u32_u24 v90, v88, s20, v102
	v_lshl_add_u32 v95, v90, 2, v135
	ds_read_b32 v91, v95
	s_waitcnt lgkmcnt(1)
	v_lshlrev_b32_e32 v88, 16, v89
	v_and_b32_e32 v89, 0xffff0000, v89
	v_pk_add_f32 v[92:93], v[88:89], 1.0 op_sel_hi:[1,0] neg_lo:[1,0] neg_hi:[1,0]
	s_waitcnt lgkmcnt(0)
	v_lshlrev_b32_e32 v90, 16, v91
	v_pk_mul_f32 v[84:85], v[84:85], v[92:93]
	v_and_b32_e32 v91, 0xffff0000, v91
	v_max_f32_e32 v92, 0xda24260, v84
	v_max_f32_e32 v93, 0xda24260, v85
	v_rcp_f32_e32 v92, v92
	v_rcp_f32_e32 v93, v93
	s_nop 0
	v_pk_mul_f32 v[88:89], v[92:93], v[88:89]
	s_nop 0
	v_cvt_pk_bf16_f32 v88, v88, v89
	ds_write_b32 v94, v88
	v_pk_mul_f32 v[88:89], v[84:85], v[90:91]
	s_nop 0
	v_cvt_pk_bf16_f32 v88, v88, v89
	ds_write_b32 v95, v88
	global_load_dwordx4 v[10:13], v240, s[98:99]
	v_mul_u32_u24_e32 v88, 0x44, v87
	v_lshl_add_u32 v94, v88, 2, v113
	ds_read_b32 v89, v94
	v_mad_u32_u24 v87, v87, s20, v102
	v_lshl_add_u32 v87, v87, 2, v135
	ds_read_b32 v91, v87
	s_waitcnt lgkmcnt(1)
	v_lshlrev_b32_e32 v88, 16, v89
	v_and_b32_e32 v89, 0xffff0000, v89
	v_pk_add_f32 v[92:93], v[88:89], 1.0 op_sel_hi:[1,0] neg_lo:[1,0] neg_hi:[1,0]
	s_waitcnt lgkmcnt(0)
	v_lshlrev_b32_e32 v90, 16, v91
	v_pk_mul_f32 v[84:85], v[84:85], v[92:93]
	v_and_b32_e32 v91, 0xffff0000, v91
	v_max_f32_e32 v92, 0xda24260, v84
	v_max_f32_e32 v93, 0xda24260, v85
	v_rcp_f32_e32 v92, v92
	v_rcp_f32_e32 v93, v93
	s_nop 0
	v_pk_mul_f32 v[88:89], v[92:93], v[88:89]
	s_nop 0
	v_cvt_pk_bf16_f32 v88, v88, v89
	ds_write_b32 v94, v88
	v_pk_mul_f32 v[88:89], v[84:85], v[90:91]
	s_nop 0
	v_cvt_pk_bf16_f32 v88, v88, v89
	ds_write_b32 v87, v88
	v_mul_u32_u24_e32 v87, 0x44, v86
	v_lshl_add_u32 v92, v87, 2, v113
	ds_read_b32 v87, v92
	v_mad_u32_u24 v88, v86, s20, v102
	v_lshl_add_u32 v93, v88, 2, v135
	ds_read_b32 v89, v93
	s_waitcnt lgkmcnt(1)
	v_lshlrev_b32_e32 v86, 16, v87
	v_and_b32_e32 v87, 0xffff0000, v87
	v_pk_add_f32 v[90:91], v[86:87], 1.0 op_sel_hi:[1,0] neg_lo:[1,0] neg_hi:[1,0]
	s_waitcnt lgkmcnt(0)
	v_lshlrev_b32_e32 v88, 16, v89
	v_pk_mul_f32 v[84:85], v[84:85], v[90:91]
	v_and_b32_e32 v89, 0xffff0000, v89
	v_max_f32_e32 v90, 0xda24260, v84
	v_max_f32_e32 v91, 0xda24260, v85
	v_rcp_f32_e32 v90, v90
	v_rcp_f32_e32 v91, v91
	v_pk_mul_f32 v[84:85], v[84:85], v[88:89]
	v_pk_mul_f32 v[86:87], v[90:91], v[86:87]
	s_nop 0
	v_cvt_pk_bf16_f32 v86, v86, v87
	v_cvt_pk_bf16_f32 v84, v84, v85
	ds_write_b32 v92, v86
	ds_write_b32 v93, v84
	global_load_dwordx4 v[14:17], v241, s[98:99]
	s_waitcnt lgkmcnt(0)
	s_barrier
	ds_read_b128 v[84:87], v136
	ds_read_b128 v[88:91], v147
	ds_read_b128 v[92:95], v147 offset:4352
	ds_read_b128 v[168:171], v147 offset:8704
	ds_read_b128 v[172:175], v176
	s_waitcnt lgkmcnt(3)
	v_mfma_f32_16x16x32_bf16 v[88:91], v[84:87], v[88:91], 0
	s_waitcnt lgkmcnt(2)
	v_mfma_f32_16x16x32_bf16 v[92:95], v[84:87], v[92:95], 0
	s_waitcnt lgkmcnt(1)
	v_mfma_f32_16x16x32_bf16 v[168:171], v[84:87], v[168:171], 0
	s_waitcnt lgkmcnt(0)
	v_mfma_f32_16x16x32_bf16 v[84:87], v[84:87], v[172:175], 0
	ds_read_b128 v[172:175], v136 offset:64
	ds_read_b128 v[198:201], v147 offset:64
	s_waitcnt lgkmcnt(0)
	v_mfma_f32_16x16x32_bf16 v[88:91], v[172:175], v[198:201], v[88:91]
	ds_read_b128 v[198:201], v147 offset:4416
	s_waitcnt lgkmcnt(0)
	v_mfma_f32_16x16x32_bf16 v[92:95], v[172:175], v[198:201], v[92:95]
	ds_read_b128 v[198:201], v147 offset:8768
	s_waitcnt lgkmcnt(0)
	v_mfma_f32_16x16x32_bf16 v[168:171], v[172:175], v[198:201], v[168:171]
	ds_read_b128 v[198:201], v176 offset:64
	s_waitcnt lgkmcnt(0)
	v_mfma_f32_16x16x32_bf16 v[84:87], v[172:175], v[198:201], v[84:87]
	ds_read_b128 v[172:175], v136 offset:128
	ds_read_b128 v[198:201], v147 offset:128
	s_waitcnt lgkmcnt(0)
	global_load_dwordx4 v[26:29], v242, s[98:99]
	v_mfma_f32_16x16x32_bf16 v[88:91], v[172:175], v[198:201], v[88:91]
	ds_read_b128 v[198:201], v147 offset:4480
	s_waitcnt lgkmcnt(0)
	v_mfma_f32_16x16x32_bf16 v[92:95], v[172:175], v[198:201], v[92:95]
	ds_read_b128 v[198:201], v147 offset:8832
	s_waitcnt lgkmcnt(0)
	v_mfma_f32_16x16x32_bf16 v[168:171], v[172:175], v[198:201], v[168:171]
	ds_read_b128 v[198:201], v176 offset:128
	s_waitcnt lgkmcnt(0)
	v_mfma_f32_16x16x32_bf16 v[84:87], v[172:175], v[198:201], v[84:87]
	ds_read_b128 v[172:175], v136 offset:192
	ds_read_b128 v[198:201], v147 offset:192
	s_waitcnt lgkmcnt(0)
	v_mfma_f32_16x16x32_bf16 v[88:91], v[172:175], v[198:201], v[88:91]
	ds_read_b128 v[198:201], v147 offset:4544
	s_waitcnt lgkmcnt(0)
	v_mfma_f32_16x16x32_bf16 v[92:95], v[172:175], v[198:201], v[92:95]
	ds_read_b128 v[198:201], v147 offset:8896
	s_nop 3
	v_cvt_pk_bf16_f32 v88, v88, s0
	v_cvt_pk_bf16_f32 v89, v89, s0
	s_waitcnt lgkmcnt(0)
	v_mfma_f32_16x16x32_bf16 v[168:171], v[172:175], v[198:201], v[168:171]
	ds_read_b128 v[198:201], v176 offset:192
	v_cvt_pk_bf16_f32 v90, v90, s0
	v_cvt_pk_bf16_f32 v91, v91, s0
	v_cndmask_b32_e64 v88, 0, v88, s[42:43]
	v_cndmask_b32_e64 v89, 0, v89, s[44:45]
	v_cndmask_b32_e64 v90, 0, v90, s[46:47]
	v_cndmask_b32_e64 v91, 0, v91, s[48:49]
	s_waitcnt lgkmcnt(0)
	v_mfma_f32_16x16x32_bf16 v[84:87], v[172:175], v[198:201], v[84:87]
	v_perm_b32 v88, v89, v88, s21
	v_perm_b32 v89, v91, v90, s21
	v_add_u32_e32 v90, v138, v75
	global_load_dwordx4 v[30:33], v243, s[98:99]
	ds_write_b64 v90, v[88:89]
	v_cvt_pk_bf16_f32 v88, v92, s0
	v_cvt_pk_bf16_f32 v89, v93, s0
	v_cvt_pk_bf16_f32 v91, v94, s0
	v_cvt_pk_bf16_f32 v92, v95, s0
	v_cndmask_b32_e64 v88, 0, v88, s[50:51]
	v_cndmask_b32_e64 v89, 0, v89, s[52:53]
	v_cndmask_b32_e64 v91, 0, v91, s[54:55]
	v_cndmask_b32_e64 v92, 0, v92, s[56:57]
	v_perm_b32 v88, v89, v88, s21
	v_perm_b32 v89, v92, v91, s21
	ds_write_b64 v90, v[88:89] offset:2304
	v_cvt_pk_bf16_f32 v88, v168, s0
	v_cvt_pk_bf16_f32 v89, v169, s0
	v_cvt_pk_bf16_f32 v91, v170, s0
	v_cvt_pk_bf16_f32 v92, v171, s0
	v_cvt_pk_bf16_f32 v84, v84, s0
	v_cvt_pk_bf16_f32 v85, v85, s0
	v_cvt_pk_bf16_f32 v86, v86, s0
	v_cvt_pk_bf16_f32 v87, v87, s0
	v_cndmask_b32_e64 v88, 0, v88, s[58:59]
	v_cndmask_b32_e64 v89, 0, v89, s[60:61]
	v_cndmask_b32_e64 v91, 0, v91, s[62:63]
	v_cndmask_b32_e64 v92, 0, v92, s[64:65]
	v_cndmask_b32_e64 v84, 0, v84, s[66:67]
	v_cndmask_b32_e64 v85, 0, v85, s[68:69]
	v_cndmask_b32_e64 v86, 0, v86, s[70:71]
	v_cndmask_b32_e64 v87, 0, v87, s[72:73]
	v_perm_b32 v88, v89, v88, s21
	v_perm_b32 v89, v92, v91, s21
	v_perm_b32 v84, v85, v84, s21
	v_perm_b32 v85, v87, v86, s21
	v_add_u32_e32 v86, v138, v96
	ds_write_b64 v90, v[88:89] offset:4608
	ds_write_b64 v86, v[84:85]
	s_waitcnt lgkmcnt(0)
	s_barrier
	ds_read_b64_tr_b16 v[84:85], v164
	ds_read_b64_tr_b16 v[86:87], v164 offset:1088
	ds_read_b128 v[88:91], v139
	ds_read_b128 v[92:95], v140
	s_waitcnt lgkmcnt(1)
	v_mfma_f32_16x16x32_bf16 v[88:91], v[88:91], v[84:87], 0
	v_add_u32_e32 v147, v106, v71
	v_add_u32_e32 v176, v106, v73
	s_waitcnt lgkmcnt(0)
	v_mfma_f32_16x16x32_bf16 v[88:91], v[92:95], v[84:87], v[88:91]
	ds_read_b128 v[92:95], v141
	ds_read_b128 v[168:171], v142
	s_waitcnt lgkmcnt(1)
	v_mfma_f32_16x16x32_bf16 v[92:95], v[92:95], v[84:87], 0
	s_waitcnt lgkmcnt(0)
	v_mfma_f32_16x16x32_bf16 v[92:95], v[168:171], v[84:87], v[92:95]
	ds_read_b128 v[168:171], v143
	ds_read_b128 v[172:175], v144
	s_waitcnt lgkmcnt(1)
	v_mfma_f32_16x16x32_bf16 v[168:171], v[168:171], v[84:87], 0
	s_waitcnt lgkmcnt(0)
	v_mfma_f32_16x16x32_bf16 v[168:171], v[172:175], v[84:87], v[168:171]
	ds_read_b128 v[172:175], v145
	ds_read_b128 v[198:201], v152
	s_waitcnt lgkmcnt(1)
	v_mfma_f32_16x16x32_bf16 v[172:175], v[172:175], v[84:87], 0
	s_waitcnt lgkmcnt(0)
	v_mfma_f32_16x16x32_bf16 v[84:87], v[198:201], v[84:87], v[172:175]
	s_nop 5
	ds_read_b64_tr_b16 v[172:173], v165
	ds_read_b64_tr_b16 v[174:175], v165 offset:1088
	ds_read_b128 v[198:201], v153
	ds_read_b128 v[202:205], v154
	s_waitcnt lgkmcnt(1)
	v_mfma_f32_16x16x32_bf16 v[88:91], v[198:201], v[172:175], v[88:91]
	s_waitcnt lgkmcnt(0)
	v_mfma_f32_16x16x32_bf16 v[88:91], v[202:205], v[172:175], v[88:91]
	ds_read_b128 v[198:201], v155
	ds_read_b128 v[202:205], v156
	s_waitcnt lgkmcnt(1)
	v_mfma_f32_16x16x32_bf16 v[92:95], v[198:201], v[172:175], v[92:95]
	s_waitcnt lgkmcnt(0)
	v_mfma_f32_16x16x32_bf16 v[92:95], v[202:205], v[172:175], v[92:95]
	ds_read_b128 v[198:201], v157
	ds_read_b128 v[202:205], v158
	s_waitcnt lgkmcnt(1)
	v_mfma_f32_16x16x32_bf16 v[168:171], v[198:201], v[172:175], v[168:171]
	s_waitcnt lgkmcnt(0)
	v_mfma_f32_16x16x32_bf16 v[168:171], v[202:205], v[172:175], v[168:171]
	ds_read_b128 v[198:201], v159
	ds_read_b128 v[202:205], v160
	s_waitcnt lgkmcnt(1)
	v_mfma_f32_16x16x32_bf16 v[84:87], v[198:201], v[172:175], v[84:87]
	s_waitcnt lgkmcnt(0)
	v_mfma_f32_16x16x32_bf16 v[84:87], v[202:205], v[172:175], v[84:87]
	ds_read_b128 v[172:175], v147
	s_waitcnt vmcnt(15) lgkmcnt(0)
	v_mfma_f32_16x16x32_bf16 v[88:91], v[172:175], v[62:65], v[88:91]
	ds_read_b128 v[172:175], v147 offset:4352
	s_waitcnt lgkmcnt(0)
	v_mfma_f32_16x16x32_bf16 v[92:95], v[172:175], v[62:65], v[92:95]
	ds_read_b128 v[172:175], v147 offset:8704
	s_waitcnt lgkmcnt(0)
	v_mfma_f32_16x16x32_bf16 v[168:171], v[172:175], v[62:65], v[168:171]
	ds_read_b128 v[172:175], v176
	s_waitcnt lgkmcnt(0)
	v_mfma_f32_16x16x32_bf16 v[62:65], v[172:175], v[62:65], v[84:87]
	s_nop 2
	ds_read_b128 v[84:87], v147 offset:64
	s_waitcnt vmcnt(14) lgkmcnt(0)
	v_mfma_f32_16x16x32_bf16 v[84:87], v[84:87], v[58:61], v[88:91]
	s_nop 2
	ds_read_b128 v[88:91], v147 offset:4416
	s_waitcnt lgkmcnt(0)
	v_mfma_f32_16x16x32_bf16 v[88:91], v[88:91], v[58:61], v[92:95]
	s_nop 2
	ds_read_b128 v[92:95], v147 offset:8768
	s_waitcnt lgkmcnt(0)
	v_mfma_f32_16x16x32_bf16 v[92:95], v[92:95], v[58:61], v[168:171]
	s_nop 2
	ds_read_b128 v[168:171], v176 offset:64
	s_waitcnt lgkmcnt(0)
	v_mfma_f32_16x16x32_bf16 v[58:61], v[168:171], v[58:61], v[62:65]
	s_nop 2
	ds_read_b128 v[62:65], v147 offset:128
	v_lshl_add_u64 v[168:169], v[80:81], 0, s[80:81]
	s_lshl_b32 s80, s14, 8
	s_waitcnt vmcnt(13) lgkmcnt(0)
	v_mfma_f32_16x16x32_bf16 v[62:65], v[62:65], v[54:57], v[84:87]
	s_nop 2
	ds_read_b128 v[84:87], v147 offset:4480
	s_waitcnt lgkmcnt(0)
	v_mfma_f32_16x16x32_bf16 v[84:87], v[84:87], v[54:57], v[88:91]
	s_nop 2
	ds_read_b128 v[88:91], v147 offset:8832
	s_waitcnt lgkmcnt(0)
	v_mfma_f32_16x16x32_bf16 v[88:91], v[88:91], v[54:57], v[92:95]
	s_nop 2
	ds_read_b128 v[92:95], v176 offset:128
	s_waitcnt lgkmcnt(0)
	v_mfma_f32_16x16x32_bf16 v[54:57], v[92:95], v[54:57], v[58:61]
	s_nop 2
	ds_read_b128 v[58:61], v147 offset:192
	s_waitcnt vmcnt(12) lgkmcnt(0)
	v_mfma_f32_16x16x32_bf16 v[58:61], v[58:61], v[50:53], v[62:65]
	s_nop 2
	ds_read_b128 v[62:65], v147 offset:4544
	s_waitcnt lgkmcnt(0)
	v_mfma_f32_16x16x32_bf16 v[62:65], v[62:65], v[50:53], v[84:87]
	s_nop 2
	ds_read_b128 v[84:87], v147 offset:8896
	s_waitcnt lgkmcnt(0)
	v_mfma_f32_16x16x32_bf16 v[84:87], v[84:87], v[50:53], v[88:91]
	s_nop 2
	ds_read_b128 v[88:91], v176 offset:192
	s_waitcnt lgkmcnt(0)
	v_mfma_f32_16x16x32_bf16 v[50:53], v[88:91], v[50:53], v[54:57]
	s_nop 2
	ds_read_b128 v[54:57], v147 offset:17408
	s_waitcnt vmcnt(11) lgkmcnt(0)
	v_mfma_f32_16x16x32_bf16 v[54:57], v[54:57], v[46:49], v[58:61]
	s_nop 2
	ds_read_b128 v[58:61], v147 offset:21760
	s_waitcnt lgkmcnt(0)
	v_mfma_f32_16x16x32_bf16 v[58:61], v[58:61], v[46:49], v[62:65]
	s_nop 2
	ds_read_b128 v[62:65], v147 offset:26112
	s_waitcnt lgkmcnt(0)
	v_mfma_f32_16x16x32_bf16 v[62:65], v[62:65], v[46:49], v[84:87]
	s_nop 2
	ds_read_b128 v[84:87], v176 offset:17408
	s_waitcnt lgkmcnt(0)
	v_mfma_f32_16x16x32_bf16 v[46:49], v[84:87], v[46:49], v[50:53]
	s_nop 2
	ds_read_b128 v[50:53], v147 offset:17472
	s_waitcnt vmcnt(10) lgkmcnt(0)
	v_mfma_f32_16x16x32_bf16 v[50:53], v[50:53], v[42:45], v[54:57]
	s_nop 2
	ds_read_b128 v[54:57], v147 offset:21824
	s_waitcnt lgkmcnt(0)
	v_mfma_f32_16x16x32_bf16 v[54:57], v[54:57], v[42:45], v[58:61]
	s_nop 2
	ds_read_b128 v[58:61], v147 offset:26176
	s_waitcnt lgkmcnt(0)
	v_mfma_f32_16x16x32_bf16 v[58:61], v[58:61], v[42:45], v[62:65]
	s_nop 2
	ds_read_b128 v[62:65], v176 offset:17472
	s_waitcnt lgkmcnt(0)
	v_mfma_f32_16x16x32_bf16 v[42:45], v[62:65], v[42:45], v[46:49]
	s_nop 2
	ds_read_b128 v[46:49], v147 offset:17536
	s_waitcnt vmcnt(9) lgkmcnt(0)
	v_mfma_f32_16x16x32_bf16 v[46:49], v[46:49], v[38:41], v[50:53]
	s_nop 2
	ds_read_b128 v[50:53], v147 offset:21888
	s_waitcnt lgkmcnt(0)
	v_mfma_f32_16x16x32_bf16 v[50:53], v[50:53], v[38:41], v[54:57]
	s_nop 2
	ds_read_b128 v[54:57], v147 offset:26240
	s_waitcnt lgkmcnt(0)
	v_mfma_f32_16x16x32_bf16 v[54:57], v[54:57], v[38:41], v[58:61]
	s_nop 2
	ds_read_b128 v[58:61], v176 offset:17536
	s_waitcnt lgkmcnt(0)
	v_mfma_f32_16x16x32_bf16 v[38:41], v[58:61], v[38:41], v[42:45]
	s_nop 2
	ds_read_b128 v[42:45], v147 offset:17600
	v_lshl_add_u64 v[58:59], vcc, 0, v[76:77]
	s_waitcnt vmcnt(8) lgkmcnt(0)
	v_mfma_f32_16x16x32_bf16 v[42:45], v[42:45], v[34:37], v[46:49]
	s_nop 2
	ds_read_b128 v[46:49], v147 offset:21952
	s_waitcnt lgkmcnt(0)
	v_mfma_f32_16x16x32_bf16 v[46:49], v[46:49], v[34:37], v[50:53]
	s_nop 2
	ds_read_b128 v[50:53], v147 offset:26304
	s_waitcnt lgkmcnt(0)
	v_mfma_f32_16x16x32_bf16 v[50:53], v[50:53], v[34:37], v[54:57]
	s_nop 2
	ds_read_b128 v[54:57], v176 offset:17600
	s_waitcnt lgkmcnt(0)
	v_mfma_f32_16x16x32_bf16 v[38:41], v[54:57], v[34:37], v[38:41]
	v_lshlrev_b64 v[34:35], 8, v[58:59]
	v_lshl_add_u64 v[34:35], s[16:17], 0, v[34:35]
	v_lshl_add_u64 v[34:35], v[34:35], 0, v[0:1]
	s_mov_b64 s[16:17], 0x10000000
	v_lshl_add_u64 v[36:37], v[34:35], 0, s[16:17]
	v_add_co_u32_e32 v34, vcc, s15, v34
	v_lshlrev_b64 v[58:59], 11, v[58:59]
	s_nop 0
	v_addc_co_u32_e32 v35, vcc, 0, v35, vcc
	global_load_dwordx4 v[54:57], v[34:35], off
	s_nop 0
	global_load_dwordx4 v[34:37], v[36:37], off offset:16
	s_barrier
	ds_write2_b32 v166, v42, v43 offset1:132
	v_add_u32_e32 v42, 0x400, v166
	ds_write2_b32 v42, v44, v45 offset0:8 offset1:140
	v_add_u32_e32 v42, 0x2000, v166
	ds_write2_b32 v42, v46, v47 offset0:64 offset1:196
	v_add_u32_e32 v42, 0x2400, v166
	ds_write2_b32 v42, v48, v49 offset0:72 offset1:204
	v_add_u32_e32 v42, 0x4200, v166
	ds_write2_b32 v42, v50, v51 offset1:132
	v_add_u32_e32 v42, 0x4600, v166
	ds_write2_b32 v42, v52, v53 offset0:8 offset1:140
	v_add_u32_e32 v42, 0x6200, v166
	ds_write2_b32 v42, v38, v39 offset0:64 offset1:196
	v_add_u32_e32 v38, 0x6600, v166
	ds_write2_b32 v38, v40, v41 offset0:72 offset1:204
	s_waitcnt lgkmcnt(0)
	s_barrier
	ds_read_b128 v[50:53], v162
	ds_read_b128 v[46:49], v162 offset:16
	ds_read_b128 v[42:45], v162 offset:32
	ds_read_b128 v[38:41], v162 offset:48
	v_lshl_add_u64 v[58:59], s[74:75], 0, v[58:59]
	s_waitcnt lgkmcnt(3)
	v_pk_mul_f32 v[60:61], v[52:53], v[52:53]
	v_pk_mul_f32 v[62:63], v[50:51], v[50:51]
	v_lshl_add_u64 v[58:59], v[58:59], 0, s[80:81]
	v_pk_mov_b32 v[64:65], v[62:63], v[60:61] op_sel:[1,0]
	v_mov_b32_e32 v63, v61
	v_pk_add_f32 v[60:61], v[64:65], v[62:63]
	s_waitcnt lgkmcnt(2)
	v_pk_mul_f32 v[62:63], v[48:49], v[48:49]
	v_pk_mul_f32 v[64:65], v[46:47], v[46:47]
	v_pk_add_f32 v[60:61], v[60:61], v[60:61] op_sel:[0,1] op_sel_hi:[1,0]
	v_pk_mov_b32 v[84:85], v[64:65], v[62:63] op_sel:[1,0]
	v_mov_b32_e32 v65, v63
	v_pk_add_f32 v[62:63], v[84:85], v[64:65]
	s_waitcnt lgkmcnt(0)
	v_mul_f32_e32 v64, v38, v38
	v_mul_f32_e32 v65, v39, v39
	v_pk_add_f32 v[62:63], v[62:63], v[62:63] op_sel:[0,1] op_sel_hi:[1,0]
	v_mov_b32_e32 v61, v64
	v_mov_b32_e32 v63, v65
	v_pk_add_f32 v[60:61], v[60:61], v[62:63]
	v_mul_f32_e32 v62, v43, v43
	v_mul_f32_e32 v64, v45, v45
	v_mul_f32_e32 v84, v40, v40
	v_mul_f32_e32 v85, v41, v41
	v_pk_fma_f32 v[62:63], v[42:43], v[42:43], v[62:63] op_sel_hi:[1,1,0]
	v_pk_fma_f32 v[64:65], v[44:45], v[44:45], v[64:65] op_sel_hi:[1,1,0]
	v_mov_b32_e32 v63, v84
	v_mov_b32_e32 v65, v85
	v_pk_add_f32 v[62:63], v[62:63], v[64:65]
	v_lshl_add_u64 v[86:87], v[58:59], 0, v[0:1]
	v_pk_add_f32 v[60:61], v[60:61], v[62:63]
	s_waitcnt vmcnt(1)
	v_lshlrev_b32_e32 v92, 16, v54
	v_add_f32_e32 v60, v60, v61
	ds_bpermute_b32 v61, v97, v60
	v_and_b32_e32 v93, 0xffff0000, v54
	v_lshlrev_b32_e32 v94, 16, v55
	v_and_b32_e32 v95, 0xffff0000, v55
	v_lshlrev_b32_e32 v88, 16, v56
	s_waitcnt lgkmcnt(0)
	v_add_f32_e32 v60, v60, v61
	ds_bpermute_b32 v61, v98, v60
	v_and_b32_e32 v89, 0xffff0000, v56
	v_lshlrev_b32_e32 v90, 16, v57
	v_and_b32_e32 v91, 0xffff0000, v57
	s_waitcnt lgkmcnt(0)
	v_add_f32_e32 v60, v60, v61
	ds_bpermute_b32 v61, v163, v60
	s_waitcnt lgkmcnt(0)
	v_add_f32_e32 v60, v60, v61
	v_fmamk_f32 v60, v60, 0x3c000000, v178
	v_cmp_gt_f32_e32 vcc, s22, v60
	v_mul_f32_e32 v61, 0x4b800000, v60
	s_nop 0
	v_cndmask_b32_e32 v60, v60, v61, vcc
	v_rsq_f32_e32 v60, v60
	s_nop 0
	v_mul_f32_e32 v61, 0x45800000, v60
	v_cndmask_b32_e32 v84, v60, v61, vcc
	v_pk_mul_f32 v[52:53], v[52:53], v[84:85] op_sel_hi:[1,0]
	v_pk_mul_f32 v[50:51], v[50:51], v[84:85] op_sel_hi:[1,0]
	v_pk_mul_f32 v[48:49], v[48:49], v[84:85] op_sel_hi:[1,0]
	v_pk_mul_f32 v[46:47], v[46:47], v[84:85] op_sel_hi:[1,0]
	v_pk_mul_f32 v[44:45], v[44:45], v[84:85] op_sel_hi:[1,0]
	v_pk_mul_f32 v[42:43], v[42:43], v[84:85] op_sel_hi:[1,0]
	v_pk_mul_f32 v[40:41], v[40:41], v[84:85] op_sel_hi:[1,0]
	v_pk_mul_f32 v[38:39], v[38:39], v[84:85] op_sel_hi:[1,0]
	s_and_b64 vcc, exec, s[12:13]
	v_pk_mul_f32 v[38:39], v[232:233], v[38:39]
	v_pk_mul_f32 v[42:43], v[228:229], v[42:43]
	v_pk_mul_f32 v[46:47], v[224:225], v[46:47]
	v_pk_mul_f32 v[50:51], v[220:221], v[50:51]
	v_pk_mul_f32 v[52:53], v[222:223], v[52:53]
	v_pk_mul_f32 v[48:49], v[226:227], v[48:49]
	v_pk_mul_f32 v[52:53], v[52:53], v[94:95]
	v_pk_mul_f32 v[50:51], v[50:51], v[92:93]
	v_pk_mul_f32 v[62:63], v[48:49], v[90:91]
	v_pk_mul_f32 v[48:49], v[46:47], v[88:89]
	v_cvt_pk_bf16_f32 v46, v50, v51
	v_cvt_pk_bf16_f32 v47, v52, v53
	v_cvt_pk_bf16_f32 v48, v48, v49
	v_cvt_pk_bf16_f32 v49, v62, v63
	global_store_dwordx4 v[86:87], v[46:49], off offset:1024
	v_pk_mul_f32 v[44:45], v[230:231], v[44:45]
	v_pk_mul_f32 v[40:41], v[234:235], v[40:41]
	s_waitcnt vmcnt(1)
	v_lshlrev_b32_e32 v46, 16, v34
	v_and_b32_e32 v47, 0xffff0000, v34
	v_lshlrev_b32_e32 v34, 16, v35
	v_and_b32_e32 v35, 0xffff0000, v35
	v_lshlrev_b32_e32 v48, 16, v36
	v_and_b32_e32 v49, 0xffff0000, v36
	v_lshlrev_b32_e32 v36, 16, v37
	v_and_b32_e32 v37, 0xffff0000, v37
	v_pk_mul_f32 v[44:45], v[44:45], v[34:35]
	v_pk_mul_f32 v[34:35], v[42:43], v[46:47]
	v_pk_mul_f32 v[40:41], v[40:41], v[36:37]
	v_pk_mul_f32 v[36:37], v[38:39], v[48:49]
	v_cvt_pk_bf16_f32 v34, v34, v35
	v_cvt_pk_bf16_f32 v35, v44, v45
	v_cvt_pk_bf16_f32 v36, v36, v37
	v_cvt_pk_bf16_f32 v37, v40, v41
	global_store_dwordx4 v[86:87], v[34:37], off offset:1040
	s_barrier
	s_cbranch_vccnz .LBB0_455
.LBB0_445:
	s_add_i32 s28, s29, s2
	s_cmpk_gt_i32 s28, 0x7ff
	s_cselect_b64 s[12:13], -1, 0
	s_waitcnt vmcnt(11)
	ds_write_b128 v109, v[2:5]
	ds_write_b128 v109, v[2:5] offset:17408
	s_waitcnt vmcnt(10)
	ds_write_b128 v109, v[6:9] offset:34816
	s_waitcnt vmcnt(9)
	ds_write_b128 v109, v[18:21] offset:52224
	s_waitcnt vmcnt(8)
	ds_write_b128 v110, v[22:25]
	s_waitcnt vmcnt(7)
	ds_write_b128 v111, v[10:13]
	ds_write_b128 v111, v[10:13] offset:17408
	s_waitcnt vmcnt(6)
	ds_write_b128 v111, v[14:17] offset:34816
	s_waitcnt vmcnt(5)
	ds_write_b128 v111, v[26:29] offset:52224
	s_waitcnt vmcnt(4)
	ds_write_b128 v112, v[30:33]
	s_waitcnt lgkmcnt(0)
	s_barrier
	s_cmpk_lt_i32 s28, 0x800
	s_cselect_b32 s100, s28, s29
	s_lshr_b32 s101, s100, 2
	s_lshl_b32 s101, s101, 14
	s_and_b32 s100, s100, 3
	s_lshl_b32 s100, s100, 23
	s_add_u32 s100, s100, s101
	s_add_u32 s100, s100, 0x8000000
	s_add_u32 s98, s86, s100
	s_addc_u32 s99, s87, 0
.LBB0_447:
	s_movk_i32 s14, 0x8000
	v_add_co_u32_e32 v34, vcc, s14, v82
	v_readfirstlane_b32 s14, v70
	s_nop 0
	v_addc_co_u32_e32 v35, vcc, -1, v83, vcc
	s_and_b32 s100, s29, 3
	s_lshl_b32 s100, s100, 9
	s_mov_b32 s101, 0
	v_lshl_add_u64 v[244:245], v[80:81], 0, s[100:101]
	global_load_dwordx4 v[220:223], v[244:245], off
	global_load_dwordx4 v[224:227], v[244:245], off offset:16
	global_load_dwordx4 v[228:231], v[244:245], off offset:32
	global_load_dwordx4 v[232:235], v[244:245], off offset:48
	global_load_dwordx4 v[62:65], v[34:35], off offset:-192
	s_bfe_u32 s16, s14, 0x20006
	s_lshl_b32 s14, s16, 4
	s_or_b32 s15, s14, 15
	v_mov_b32_e32 v197, s15
	v_mov_b32_e32 v200, s14
	v_cndmask_b32_e64 v173, v197, v200, s[40:41]
	v_or_b32_e32 v172, s14, v115
	v_or_b32_e32 v171, s14, v118
	v_or_b32_e32 v170, s14, v119
	v_mad_u32_u24 v84, v173, s18, v113
	v_mad_u32_u24 v85, v172, s18, v113
	v_mad_u32_u24 v86, v171, s18, v113
	v_mad_u32_u24 v87, v170, s18, v113
	v_or_b32_e32 v169, s14, v120
	v_or_b32_e32 v168, s14, v121
	v_or_b32_e32 v95, s14, v122
	v_or_b32_e32 v94, s14, v123
	v_mad_u32_u24 v88, v169, s18, v113
	v_mad_u32_u24 v89, v168, s18, v113
	v_mad_u32_u24 v90, v95, s18, v113
	v_mad_u32_u24 v91, v94, s18, v113
	ds_read_b32 v92, v84
	ds_read_b32 v93, v85
	ds_read_b32 v147, v86
	ds_read_b32 v174, v87
	ds_read_b32 v175, v88
	ds_read_b32 v176, v89
	ds_read_b32 v177, v90
	ds_read_b32 v199, v91
	global_load_dwordx4 v[58:61], v[34:35], off offset:-128
	s_waitcnt lgkmcnt(7)
	v_lshlrev_b32_e32 v84, 16, v92
	v_and_b32_e32 v85, 0xffff0000, v92
	s_waitcnt lgkmcnt(6)
	v_lshlrev_b32_e32 v86, 16, v93
	v_and_b32_e32 v87, 0xffff0000, v93
	s_waitcnt lgkmcnt(5)
	v_lshlrev_b32_e32 v88, 16, v147
	v_and_b32_e32 v89, 0xffff0000, v147
	v_pk_add_f32 v[84:85], v[84:85], 1.0 op_sel_hi:[1,0] neg_lo:[1,0] neg_hi:[1,0]
	v_pk_add_f32 v[86:87], v[86:87], 1.0 op_sel_hi:[1,0] neg_lo:[1,0] neg_hi:[1,0]
	s_waitcnt lgkmcnt(4)
	v_lshlrev_b32_e32 v90, 16, v174
	v_and_b32_e32 v91, 0xffff0000, v174
	v_pk_mul_f32 v[84:85], v[84:85], v[86:87]
	v_pk_add_f32 v[86:87], v[88:89], 1.0 op_sel_hi:[1,0] neg_lo:[1,0] neg_hi:[1,0]
	s_waitcnt lgkmcnt(3)
	v_lshlrev_b32_e32 v92, 16, v175
	v_and_b32_e32 v93, 0xffff0000, v175
	v_pk_mul_f32 v[84:85], v[84:85], v[86:87]
	v_pk_add_f32 v[86:87], v[90:91], 1.0 op_sel_hi:[1,0] neg_lo:[1,0] neg_hi:[1,0]
	v_or_b32_e32 v91, s14, v127
	v_pk_mul_f32 v[84:85], v[84:85], v[86:87]
	v_pk_add_f32 v[86:87], v[92:93], 1.0 op_sel_hi:[1,0] neg_lo:[1,0] neg_hi:[1,0]
	v_or_b32_e32 v93, s14, v124
	v_pk_mul_f32 v[84:85], v[84:85], v[86:87]
	s_waitcnt lgkmcnt(2)
	v_lshlrev_b32_e32 v86, 16, v176
	v_and_b32_e32 v87, 0xffff0000, v176
	v_pk_add_f32 v[174:175], v[86:87], 1.0 op_sel_hi:[1,0] neg_lo:[1,0] neg_hi:[1,0]
	v_cndmask_b32_e64 v86, v200, v197, s[40:41]
	s_waitcnt lgkmcnt(1)
	v_lshlrev_b32_e32 v176, 16, v177
	v_and_b32_e32 v177, 0xffff0000, v177
	v_mad_u32_u24 v201, v93, s18, v113
	v_or_b32_e32 v92, s14, v126
	v_or_b32_e32 v90, s14, v128
	v_or_b32_e32 v89, s14, v129
	v_or_b32_e32 v88, s14, v130
	v_or_b32_e32 v87, s14, v131
	v_mad_u32_u24 v197, v86, s18, v113
	s_waitcnt lgkmcnt(0)
	v_lshlrev_b32_e32 v198, 16, v199
	v_and_b32_e32 v199, 0xffff0000, v199
	v_mad_u32_u24 v202, v92, s18, v113
	v_mad_u32_u24 v203, v91, s18, v113
	v_mad_u32_u24 v204, v90, s18, v113
	v_mad_u32_u24 v205, v89, s18, v113
	v_mad_u32_u24 v206, v88, s18, v113
	v_mad_u32_u24 v207, v87, s18, v113
	ds_read_b32 v201, v201
	ds_read_b32 v208, v202
	ds_read_b32 v209, v203
	ds_read_b32 v210, v204
	ds_read_b32 v211, v205
	ds_read_b32 v212, v206
	ds_read_b32 v213, v207
	ds_read_b32 v197, v197
	global_load_dwordx4 v[54:57], v[34:35], off offset:-64
	v_pk_mul_f32 v[84:85], v[84:85], v[174:175]
	v_pk_add_f32 v[174:175], v[176:177], 1.0 op_sel_hi:[1,0] neg_lo:[1,0] neg_hi:[1,0]
	s_waitcnt lgkmcnt(7)
	v_lshlrev_b32_e32 v200, 16, v201
	v_and_b32_e32 v201, 0xffff0000, v201
	v_pk_mul_f32 v[84:85], v[84:85], v[174:175]
	v_pk_add_f32 v[174:175], v[198:199], 1.0 op_sel_hi:[1,0] neg_lo:[1,0] neg_hi:[1,0]
	s_waitcnt lgkmcnt(6)
	v_lshlrev_b32_e32 v202, 16, v208
	v_and_b32_e32 v203, 0xffff0000, v208
	v_pk_mul_f32 v[84:85], v[84:85], v[174:175]
	v_pk_add_f32 v[174:175], v[200:201], 1.0 op_sel_hi:[1,0] neg_lo:[1,0] neg_hi:[1,0]
	s_waitcnt lgkmcnt(5)
	v_lshlrev_b32_e32 v204, 16, v209
	v_and_b32_e32 v205, 0xffff0000, v209
	v_pk_mul_f32 v[84:85], v[84:85], v[174:175]
	v_pk_add_f32 v[174:175], v[202:203], 1.0 op_sel_hi:[1,0] neg_lo:[1,0] neg_hi:[1,0]
	s_waitcnt lgkmcnt(4)
	v_lshlrev_b32_e32 v206, 16, v210
	v_and_b32_e32 v207, 0xffff0000, v210
	v_pk_mul_f32 v[84:85], v[84:85], v[174:175]
	v_pk_add_f32 v[174:175], v[204:205], 1.0 op_sel_hi:[1,0] neg_lo:[1,0] neg_hi:[1,0]
	s_waitcnt lgkmcnt(3)
	v_lshlrev_b32_e32 v208, 16, v211
	v_and_b32_e32 v209, 0xffff0000, v211
	v_pk_mul_f32 v[84:85], v[84:85], v[174:175]
	v_pk_add_f32 v[174:175], v[206:207], 1.0 op_sel_hi:[1,0] neg_lo:[1,0] neg_hi:[1,0]
	s_waitcnt lgkmcnt(2)
	v_lshlrev_b32_e32 v210, 16, v212
	v_and_b32_e32 v211, 0xffff0000, v212
	v_pk_mul_f32 v[84:85], v[84:85], v[174:175]
	v_pk_add_f32 v[174:175], v[208:209], 1.0 op_sel_hi:[1,0] neg_lo:[1,0] neg_hi:[1,0]
	s_waitcnt lgkmcnt(1)
	v_lshlrev_b32_e32 v212, 16, v213
	v_and_b32_e32 v213, 0xffff0000, v213
	v_pk_mul_f32 v[84:85], v[84:85], v[174:175]
	v_pk_add_f32 v[174:175], v[210:211], 1.0 op_sel_hi:[1,0] neg_lo:[1,0] neg_hi:[1,0]
	s_waitcnt lgkmcnt(0)
	v_lshlrev_b32_e32 v216, 16, v197
	v_and_b32_e32 v217, 0xffff0000, v197
	v_pk_mul_f32 v[84:85], v[84:85], v[174:175]
	v_pk_add_f32 v[174:175], v[212:213], 1.0 op_sel_hi:[1,0] neg_lo:[1,0] neg_hi:[1,0]
	v_or_b32_e32 v197, s16, v133
	v_pk_mul_f32 v[84:85], v[84:85], v[174:175]
	v_pk_add_f32 v[174:175], v[216:217], 1.0 op_sel_hi:[1,0] neg_lo:[1,0] neg_hi:[1,0]
	s_cmp_lg_u32 s16, 0
	v_mov_b32_e32 v147, v146
	v_lshl_add_u32 v197, v197, 9, v134
	v_pk_mul_f32 v[84:85], v[84:85], v[174:175]
	s_cselect_b64 s[14:15], -1, 0
	ds_write_b64 v197, v[84:85]
	s_and_b64 s[30:31], s[40:41], s[14:15]
	v_mov_b64_e32 v[84:85], v[146:147]
	s_waitcnt lgkmcnt(0)
	s_barrier
	s_and_saveexec_b64 s[14:15], s[30:31]
	ds_read_b64 v[84:85], v134
	s_or_b64 exec, exec, s[14:15]
	s_cmp_eq_u32 s16, 0
	s_cselect_b64 s[14:15], -1, 0
	s_cmp_gt_u32 s16, 1
	v_cndmask_b32_e64 v147, 0, 1, s[14:15]
	s_cselect_b64 s[14:15], -1, 0
	v_cndmask_b32_e64 v174, 0, 1, s[14:15]
	v_cndmask_b32_e64 v147, v147, v174, s[40:41]
	v_and_b32_e32 v147, 1, v147
	v_cmp_eq_u32_e32 vcc, 1, v147
	s_and_saveexec_b64 s[14:15], vcc
	s_cbranch_execz .LBB0_451
	ds_read_b64 v[174:175], v167 offset:512
	s_waitcnt lgkmcnt(0)
	v_pk_mul_f32 v[84:85], v[84:85], v[174:175]

	.amdhsa_kernel _Z3fwdILb1EEv4Args
		.amdhsa_group_segment_fixed_size 0
		.amdhsa_private_segment_fixed_size 0
		.amdhsa_kernarg_size 408
		.amdhsa_user_sgpr_count 2
		.amdhsa_user_sgpr_dispatch_ptr 0
		.amdhsa_user_sgpr_queue_ptr 0
		.amdhsa_user_sgpr_kernarg_segment_ptr 1
		.amdhsa_user_sgpr_dispatch_id 0
		.amdhsa_user_sgpr_kernarg_preload_length 0
		.amdhsa_user_sgpr_kernarg_preload_offset 0
		.amdhsa_user_sgpr_private_segment_size 0
		.amdhsa_uses_dynamic_stack 0
		.amdhsa_enable_private_segment 0
		.amdhsa_system_sgpr_workgroup_id_x 1
		.amdhsa_system_sgpr_workgroup_id_y 0
		.amdhsa_system_sgpr_workgroup_id_z 0
		.amdhsa_system_sgpr_workgroup_info 0
		.amdhsa_system_vgpr_workitem_id 2
		.amdhsa_next_free_vgpr 256
		.amdhsa_next_free_sgpr 102
		.amdhsa_accum_offset 256
		.amdhsa_reserve_vcc 1
		.amdhsa_float_round_mode_32 0
		.amdhsa_float_round_mode_16_64 0
		.amdhsa_float_denorm_mode_32 3
		.amdhsa_float_denorm_mode_16_64 3
		.amdhsa_dx10_clamp 1
		.amdhsa_ieee_mode 1
		.amdhsa_fp16_overflow 0
		.amdhsa_tg_split 0
		.amdhsa_exception_fp_ieee_invalid_op 0
		.amdhsa_exception_fp_denorm_src 0
		.amdhsa_exception_fp_ieee_div_zero 0
		.amdhsa_exception_fp_ieee_overflow 0
		.amdhsa_exception_fp_ieee_underflow 0
		.amdhsa_exception_fp_ieee_inexact 0
		.amdhsa_exception_int_div_zero 0
	.end_amdhsa_kernel

amdhsa.kernels:
  - .agpr_count:     0
    .args:
      - .offset:         0
        .size:           152
        .value_kind:     by_value
      - .offset:         152
        .size:           4
        .value_kind:     hidden_block_count_x
      - .offset:         156
        .size:           4
        .value_kind:     hidden_block_count_y
      - .offset:         160
        .size:           4
        .value_kind:     hidden_block_count_z
      - .offset:         164
        .size:           2
        .value_kind:     hidden_group_size_x
      - .offset:         166
        .size:           2
        .value_kind:     hidden_group_size_y
      - .offset:         168
        .size:           2
        .value_kind:     hidden_group_size_z
      - .offset:         170
        .size:           2
        .value_kind:     hidden_remainder_x
      - .offset:         172
        .size:           2
        .value_kind:     hidden_remainder_y
      - .offset:         174
        .size:           2
        .value_kind:     hidden_remainder_z
      - .offset:         192
        .size:           8
        .value_kind:     hidden_global_offset_x
      - .offset:         200
        .size:           8
        .value_kind:     hidden_global_offset_y
      - .offset:         208
        .size:           8
        .value_kind:     hidden_global_offset_z
      - .offset:         216
        .size:           2
        .value_kind:     hidden_grid_dims
      - .offset:         240
        .size:           8
        .value_kind:     hidden_multigrid_sync_arg
      - .offset:         272
        .size:           4
        .value_kind:     hidden_dynamic_lds_size
    .group_segment_fixed_size: 0
    .kernarg_segment_align: 8
    .kernarg_segment_size: 408
    .language:       OpenCL C
    .language_version:
      - 2
      - 0
    .max_flat_workgroup_size: 512
    .name:           _Z3fwdILb1EEv4Args
    .private_segment_fixed_size: 0
    .sgpr_count:     108
    .sgpr_spill_count: 115
    .symbol:         _Z3fwdILb1EEv4Args.kd
    .uniform_work_group_size: 1
    .uses_dynamic_stack: false
    .vgpr_count:     256
    .vgpr_spill_count: 0
    .wavefront_size: 64
